# v51 + out-GEMM residual epilogue: counted vmcnt waits instead of vmcnt(0) per block (no store-ack serialisation)
# speedup vs baseline: 1.0171x; 1.0171x over previous
; #define GAS __attribute__((address_space(1)))
; __device__ __forceinline__ float bf_lo(unsigned u) { return __uint_as_float(u << 16); }
; __device__ __forceinline__ float bf_hi(unsigned u) { return __uint_as_float(u & 0xffff0000u); }
; __device__ __forceinline__ v4u pack8(const f32x4 a, const f32x4 b) { v4u w; w.x = cvt_pk_bf16(a[0], a[1]); w.y = cvt_pk_bf16(a[2], a[3]); w.z = cvt_pk_bf16(b[0], b[1]); w.w = cvt_pk_bf16(b[2], b[3]); return w; }
;     __device__ __forceinline__ void operator()(Acc& acc, const Unit& u, int wr, int wc, int fr, int fq, LAS unsigned char* lds) const {
;         const int row0 = u.pm * BM + wr * 64 + fr, c0 = u.pn * BM + wc * 32 + 8 * fq; GAS bf16* HB = (GAS bf16*)(ws + WS_H);
;         const bool sample = u.pm >= MPAD / 256;
; #pragma unroll
;         for (int ai = 0; ai < 2; ++ai) {
;             v4u hb[4][2];
; #pragma unroll
;             for (int m = 0; m < 4; ++m)
; #pragma unroll
;                 for (int bj = 0; bj < 2; ++bj) hb[m][bj] = *(const GAS v4u*)(HB + (size_t)(row0 + ai * 128 + m * 16) * 1024 + c0 + bj * 128);
; #pragma unroll
;             for (int m = 0; m < 4; ++m) { const int row = row0 + ai * 128 + m * 16;
;                 if (last) { GAS float* dp; bool ok = true;
;                     if (sample) dp = out + O_YS + (size_t)(row - MPAD) * 1024 + c0;
;                     else { const int b = row / LP, t = row - b * LP; ok = row < MP && t >= NMETA; dp = out + O_YP + ((size_t)b * SEQ + (t - NMETA)) * 1024 + c0; }
;                     if (ok) {
; #pragma unroll
;                         for (int bj = 0; bj < 2; ++bj) { const v4u t = hb[m][bj];
;                             *(GAS f32x4*)(dp + bj * 128) = (f32x4){bf_lo(t.x), bf_hi(t.x), bf_lo(t.y), bf_hi(t.y)} + acc[ai][bj][m][0]; *(GAS f32x4*)(dp + bj * 128 + 4) = (f32x4){bf_lo(t.z), bf_hi(t.z), bf_lo(t.w), bf_hi(t.w)} + acc[ai][bj][m][1]; } }
;                 } else {
; #pragma unroll
;                     for (int bj = 0; bj < 2; ++bj) { const v4u t = hb[m][bj];
;                         *(GAS v4u*)(HB + (size_t)row * 1024 + c0 + bj * 128) = pack8((f32x4){bf_lo(t.x), bf_hi(t.x), bf_lo(t.y), bf_hi(t.y)} + acc[ai][bj][m][0], (f32x4){bf_lo(t.z), bf_hi(t.z), bf_lo(t.w), bf_hi(t.w)} + acc[ai][bj][m][1]); } } }
.LBB0_1190:
	v_lshl_add_u32 v182, s52, 8, v202
	v_lshl_add_u32 v170, s60, 8, v204
	v_ashrrev_i32_e32 v171, 31, v170
	v_ashrrev_i32_e32 v183, 31, v182
	v_or_b32_e32 v194, 16, v182
	v_lshl_add_u64 v[184:185], v[170:171], 1, s[12:13]
	v_lshlrev_b64 v[128:129], 11, v[182:183]
	v_ashrrev_i32_e32 v195, 31, v194
	v_or_b32_e32 v190, 32, v182
	v_lshl_add_u64 v[198:199], v[184:185], 0, v[128:129]
	v_lshlrev_b64 v[128:129], 11, v[194:195]
	v_ashrrev_i32_e32 v191, 31, v190
	v_or_b32_e32 v186, 48, v182
	v_lshl_add_u64 v[196:197], v[184:185], 0, v[128:129]
	v_lshlrev_b64 v[128:129], 11, v[190:191]
	v_ashrrev_i32_e32 v187, 31, v186
	v_lshl_add_u64 v[192:193], v[184:185], 0, v[128:129]
	v_lshlrev_b64 v[128:129], 11, v[186:187]
	v_lshl_add_u64 v[188:189], v[184:185], 0, v[128:129]
	s_mov_b32 s98, 0
	global_load_dwordx4 v[156:159], v[198:199], off
	global_load_dwordx4 v[152:155], v[198:199], off offset:256
	global_load_dwordx4 v[148:151], v[196:197], off
	global_load_dwordx4 v[144:147], v[196:197], off offset:256
	global_load_dwordx4 v[140:143], v[192:193], off
	global_load_dwordx4 v[136:139], v[192:193], off offset:256
	global_load_dwordx4 v[132:135], v[188:189], off
	global_load_dwordx4 v[128:131], v[188:189], off offset:256
	s_cmpk_lt_i32 s52, 0x41
	s_cselect_b64 s[52:53], -1, 0
	s_andn2_b64 vcc, exec, s[34:35]
	s_mov_b64 s[60:61], -1
	v_readlane_b32 s92, v240, 3
	s_cbranch_vccnz .LBB0_1192
	s_waitcnt vmcnt(6)
	v_lshlrev_b32_e32 v206, 16, v157
	v_and_b32_e32 v207, 0xffff0000, v157
	v_lshlrev_b32_e32 v200, 16, v156
	v_and_b32_e32 v201, 0xffff0000, v156
	v_pk_add_f32 v[208:209], v[126:127], v[206:207]
	v_lshlrev_b32_e32 v206, 16, v158
	v_and_b32_e32 v207, 0xffff0000, v158
	v_lshlrev_b32_e32 v218, 16, v159
	v_and_b32_e32 v219, 0xffff0000, v159
	v_pk_add_f32 v[200:201], v[124:125], v[200:201]
	v_pk_add_f32 v[218:219], v[122:123], v[218:219]
	v_pk_add_f32 v[220:221], v[120:121], v[206:207]
	v_cvt_pk_bf16_f32 v206, v200, v201
	v_cvt_pk_bf16_f32 v207, v208, v209
	v_cvt_pk_bf16_f32 v208, v220, v221
	v_cvt_pk_bf16_f32 v209, v218, v219
	global_store_dwordx4 v[198:199], v[206:209], off
	v_lshlrev_b32_e32 v200, 16, v152
	v_and_b32_e32 v201, 0xffff0000, v152
	v_lshlrev_b32_e32 v206, 16, v153
	v_and_b32_e32 v207, 0xffff0000, v153
	v_pk_add_f32 v[208:209], v[118:119], v[206:207]
	v_lshlrev_b32_e32 v206, 16, v154
	v_and_b32_e32 v207, 0xffff0000, v154
	v_lshlrev_b32_e32 v218, 16, v155
	v_and_b32_e32 v219, 0xffff0000, v155
	v_pk_add_f32 v[200:201], v[116:117], v[200:201]
	v_pk_add_f32 v[218:219], v[114:115], v[218:219]
	v_pk_add_f32 v[220:221], v[112:113], v[206:207]
	v_cvt_pk_bf16_f32 v206, v200, v201
	v_cvt_pk_bf16_f32 v207, v208, v209
	v_cvt_pk_bf16_f32 v208, v220, v221
	v_cvt_pk_bf16_f32 v209, v218, v219
	s_mov_b64 s[60:61], 0
	global_store_dwordx4 v[198:199], v[206:209], off offset:256

; #define GAS __attribute__((address_space(1)))
; __device__ __forceinline__ float bf_lo(unsigned u) { return __uint_as_float(u << 16); }
; __device__ __forceinline__ float bf_hi(unsigned u) { return __uint_as_float(u & 0xffff0000u); }
;     __device__ __forceinline__ void operator()(Acc& acc, const Unit& u, int wr, int wc, int fr, int fq, LAS unsigned char* lds) const {
;     ...
;                 if (last) { GAS float* dp; bool ok = true;
;                     if (sample) dp = out + O_YS + (size_t)(row - MPAD) * 1024 + c0;
;                     else { const int b = row / LP, t = row - b * LP; ok = row < MP && t >= NMETA; dp = out + O_YP + ((size_t)b * SEQ + (t - NMETA)) * 1024 + c0; }
;                     if (ok) {
; #pragma unroll
;                         for (int bj = 0; bj < 2; ++bj) { const v4u t = hb[m][bj];
;                             *(GAS f32x4*)(dp + bj * 128) = (f32x4){bf_lo(t.x), bf_hi(t.x), bf_lo(t.y), bf_hi(t.y)} + acc[ai][bj][m][0]; *(GAS f32x4*)(dp + bj * 128 + 4) = (f32x4){bf_lo(t.z), bf_hi(t.z), bf_lo(t.w), bf_hi(t.w)} + acc[ai][bj][m][1]; } }
.LBB0_1196:
	v_ashrrev_i32_e32 v199, 31, v198
	v_lshl_add_u64 v[200:201], s[8:9], 0, v[200:201]
	v_lshlrev_b64 v[198:199], 12, v[198:199]
	v_lshl_add_u64 v[198:199], v[200:201], 0, v[198:199]
	s_waitcnt vmcnt(6)
	v_lshlrev_b32_e32 v200, 16, v156
	v_and_b32_e32 v201, 0xffff0000, v156
	v_lshlrev_b32_e32 v156, 16, v157
	v_and_b32_e32 v157, 0xffff0000, v157
	v_lshl_add_u64 v[198:199], v[170:171], 2, v[198:199]
	v_pk_add_f32 v[126:127], v[126:127], v[156:157]
	v_pk_add_f32 v[124:125], v[124:125], v[200:201]
	global_store_dwordx4 v[198:199], v[124:127], off
	s_nop 1
	v_lshlrev_b32_e32 v124, 16, v158
	v_and_b32_e32 v125, 0xffff0000, v158
	v_lshlrev_b32_e32 v126, 16, v159
	v_and_b32_e32 v127, 0xffff0000, v159
	v_pk_add_f32 v[122:123], v[122:123], v[126:127]
	v_pk_add_f32 v[120:121], v[120:121], v[124:125]
	global_store_dwordx4 v[198:199], v[120:123], off offset:16
	s_nop 1
	v_lshlrev_b32_e32 v120, 16, v152
	v_and_b32_e32 v121, 0xffff0000, v152
	v_lshlrev_b32_e32 v122, 16, v153
	v_and_b32_e32 v123, 0xffff0000, v153
	v_pk_add_f32 v[118:119], v[118:119], v[122:123]
	v_pk_add_f32 v[116:117], v[116:117], v[120:121]
	global_store_dwordx4 v[198:199], v[116:119], off offset:512
	s_nop 1
	v_lshlrev_b32_e32 v116, 16, v154
	v_and_b32_e32 v117, 0xffff0000, v154
	v_lshlrev_b32_e32 v118, 16, v155
	v_and_b32_e32 v119, 0xffff0000, v155
	v_pk_add_f32 v[114:115], v[114:115], v[118:119]
	v_pk_add_f32 v[112:113], v[112:113], v[116:117]
	global_store_dwordx4 v[198:199], v[112:115], off offset:528
	s_bitset1_b32 s98, 0

; #define GAS __attribute__((address_space(1)))
; __device__ __forceinline__ float bf_lo(unsigned u) { return __uint_as_float(u << 16); }
; __device__ __forceinline__ float bf_hi(unsigned u) { return __uint_as_float(u & 0xffff0000u); }
;     __device__ __forceinline__ void operator()(Acc& acc, const Unit& u, int wr, int wc, int fr, int fq, LAS unsigned char* lds) const {
;     ...
;                 if (last) { GAS float* dp; bool ok = true;
;                     if (sample) dp = out + O_YS + (size_t)(row - MPAD) * 1024 + c0;
;                     else { const int b = row / LP, t = row - b * LP; ok = row < MP && t >= NMETA; dp = out + O_YP + ((size_t)b * SEQ + (t - NMETA)) * 1024 + c0; }
;                     if (ok) {
; #pragma unroll
;                         for (int bj = 0; bj < 2; ++bj) { const v4u t = hb[m][bj];
;                             *(GAS f32x4*)(dp + bj * 128) = (f32x4){bf_lo(t.x), bf_hi(t.x), bf_lo(t.y), bf_hi(t.y)} + acc[ai][bj][m][0]; *(GAS f32x4*)(dp + bj * 128 + 4) = (f32x4){bf_lo(t.z), bf_hi(t.z), bf_lo(t.w), bf_hi(t.w)} + acc[ai][bj][m][1]; } }
.LBB0_1202:
	v_ashrrev_i32_e32 v113, 31, v112
	v_lshl_add_u64 v[114:115], s[8:9], 0, v[114:115]
	v_lshlrev_b64 v[112:113], 12, v[112:113]
	v_lshl_add_u64 v[112:113], v[114:115], 0, v[112:113]
	s_cmp_eq_u32 s98, 1
	s_cbranch_scc1 .Leo_f1
	s_waitcnt vmcnt(4)
	s_branch .Leo_j1
.Leo_f1:
	s_waitcnt vmcnt(8)
.Leo_j1:
	v_lshlrev_b32_e32 v114, 16, v148
	v_and_b32_e32 v115, 0xffff0000, v148
	v_lshlrev_b32_e32 v116, 16, v149
	v_and_b32_e32 v117, 0xffff0000, v149
	v_lshl_add_u64 v[112:113], v[170:171], 2, v[112:113]
	v_pk_add_f32 v[110:111], v[110:111], v[116:117]
	v_pk_add_f32 v[108:109], v[108:109], v[114:115]
	global_store_dwordx4 v[112:113], v[108:111], off
	s_nop 1
	v_lshlrev_b32_e32 v108, 16, v150
	v_and_b32_e32 v109, 0xffff0000, v150
	v_lshlrev_b32_e32 v110, 16, v151
	v_and_b32_e32 v111, 0xffff0000, v151
	v_pk_add_f32 v[106:107], v[106:107], v[110:111]
	v_pk_add_f32 v[104:105], v[104:105], v[108:109]
	global_store_dwordx4 v[112:113], v[104:107], off offset:16
	s_nop 1
	v_lshlrev_b32_e32 v104, 16, v144
	v_and_b32_e32 v105, 0xffff0000, v144
	v_lshlrev_b32_e32 v106, 16, v145
	v_and_b32_e32 v107, 0xffff0000, v145
	v_pk_add_f32 v[102:103], v[102:103], v[106:107]
	v_pk_add_f32 v[100:101], v[100:101], v[104:105]
	global_store_dwordx4 v[112:113], v[100:103], off offset:512
	s_nop 1
	v_lshlrev_b32_e32 v100, 16, v146
	v_and_b32_e32 v101, 0xffff0000, v146
	v_lshlrev_b32_e32 v102, 16, v147
	v_and_b32_e32 v103, 0xffff0000, v147
	v_pk_add_f32 v[98:99], v[98:99], v[102:103]
	v_pk_add_f32 v[96:97], v[96:97], v[100:101]
	global_store_dwordx4 v[112:113], v[96:99], off offset:528
	s_bitset1_b32 s98, 1

; #define GAS __attribute__((address_space(1)))
; __device__ __forceinline__ float bf_lo(unsigned u) { return __uint_as_float(u << 16); }
; __device__ __forceinline__ float bf_hi(unsigned u) { return __uint_as_float(u & 0xffff0000u); }
;     __device__ __forceinline__ void operator()(Acc& acc, const Unit& u, int wr, int wc, int fr, int fq, LAS unsigned char* lds) const {
;     ...
;                 if (last) { GAS float* dp; bool ok = true;
;                     if (sample) dp = out + O_YS + (size_t)(row - MPAD) * 1024 + c0;
;                     else { const int b = row / LP, t = row - b * LP; ok = row < MP && t >= NMETA; dp = out + O_YP + ((size_t)b * SEQ + (t - NMETA)) * 1024 + c0; }
;                     if (ok) {
; #pragma unroll
;                         for (int bj = 0; bj < 2; ++bj) { const v4u t = hb[m][bj];
;                             *(GAS f32x4*)(dp + bj * 128) = (f32x4){bf_lo(t.x), bf_hi(t.x), bf_lo(t.y), bf_hi(t.y)} + acc[ai][bj][m][0]; *(GAS f32x4*)(dp + bj * 128 + 4) = (f32x4){bf_lo(t.z), bf_hi(t.z), bf_lo(t.w), bf_hi(t.w)} + acc[ai][bj][m][1]; } }
.LBB0_1208:
	v_ashrrev_i32_e32 v97, 31, v96
	v_lshl_add_u64 v[98:99], s[8:9], 0, v[98:99]
	v_lshlrev_b64 v[96:97], 12, v[96:97]
	v_lshl_add_u64 v[96:97], v[98:99], 0, v[96:97]
	s_cmp_eq_u32 s98, 3
	s_cbranch_scc1 .Leo_f2
	s_waitcnt vmcnt(2)
	s_branch .Leo_j2
.Leo_f2:
	s_waitcnt vmcnt(10)
.Leo_j2:
	v_lshlrev_b32_e32 v98, 16, v140
	v_and_b32_e32 v99, 0xffff0000, v140
	v_lshlrev_b32_e32 v100, 16, v141
	v_and_b32_e32 v101, 0xffff0000, v141
	v_lshl_add_u64 v[96:97], v[170:171], 2, v[96:97]
	v_pk_add_f32 v[94:95], v[94:95], v[100:101]
	v_pk_add_f32 v[92:93], v[92:93], v[98:99]
	global_store_dwordx4 v[96:97], v[92:95], off
	s_nop 1
	v_lshlrev_b32_e32 v92, 16, v142
	v_and_b32_e32 v93, 0xffff0000, v142
	v_lshlrev_b32_e32 v94, 16, v143
	v_and_b32_e32 v95, 0xffff0000, v143
	v_pk_add_f32 v[90:91], v[90:91], v[94:95]
	v_pk_add_f32 v[88:89], v[88:89], v[92:93]
	global_store_dwordx4 v[96:97], v[88:91], off offset:16
	s_nop 1
	v_lshlrev_b32_e32 v88, 16, v136
	v_and_b32_e32 v89, 0xffff0000, v136
	v_lshlrev_b32_e32 v90, 16, v137
	v_and_b32_e32 v91, 0xffff0000, v137
	v_pk_add_f32 v[86:87], v[86:87], v[90:91]
	v_pk_add_f32 v[84:85], v[84:85], v[88:89]
	global_store_dwordx4 v[96:97], v[84:87], off offset:512
	s_nop 1
	v_lshlrev_b32_e32 v84, 16, v138
	v_and_b32_e32 v85, 0xffff0000, v138
	v_lshlrev_b32_e32 v86, 16, v139
	v_and_b32_e32 v87, 0xffff0000, v139
	v_pk_add_f32 v[82:83], v[82:83], v[86:87]
	v_pk_add_f32 v[80:81], v[80:81], v[84:85]
	global_store_dwordx4 v[96:97], v[80:83], off offset:528
	s_bitset1_b32 s98, 2

; #define GAS __attribute__((address_space(1)))
; __device__ __forceinline__ float bf_lo(unsigned u) { return __uint_as_float(u << 16); }
; __device__ __forceinline__ float bf_hi(unsigned u) { return __uint_as_float(u & 0xffff0000u); }
; __device__ __forceinline__ v4u pack8(const f32x4 a, const f32x4 b) { v4u w; w.x = cvt_pk_bf16(a[0], a[1]); w.y = cvt_pk_bf16(a[2], a[3]); w.z = cvt_pk_bf16(b[0], b[1]); w.w = cvt_pk_bf16(b[2], b[3]); return w; }
;     __device__ __forceinline__ void operator()(Acc& acc, const Unit& u, int wr, int wc, int fr, int fq, LAS unsigned char* lds) const {
;     ...
;                 } else {
; #pragma unroll
;                     for (int bj = 0; bj < 2; ++bj) { const v4u t = hb[m][bj];
;                         *(GAS v4u*)(HB + (size_t)row * 1024 + c0 + bj * 128) = pack8((f32x4){bf_lo(t.x), bf_hi(t.x), bf_lo(t.y), bf_hi(t.y)} + acc[ai][bj][m][0], (f32x4){bf_lo(t.z), bf_hi(t.z), bf_lo(t.w), bf_hi(t.w)} + acc[ai][bj][m][1]); } } }
.LBB0_1212:
	s_waitcnt vmcnt(6)
	v_lshlrev_b32_e32 v112, 16, v148
	v_and_b32_e32 v113, 0xffff0000, v148
	v_lshlrev_b32_e32 v114, 16, v149
	v_and_b32_e32 v115, 0xffff0000, v149
	v_lshlrev_b32_e32 v116, 16, v150
	v_and_b32_e32 v117, 0xffff0000, v150
	v_lshlrev_b32_e32 v118, 16, v151
	v_and_b32_e32 v119, 0xffff0000, v151
	v_pk_add_f32 v[114:115], v[110:111], v[114:115]
	v_pk_add_f32 v[112:113], v[108:109], v[112:113]
	v_pk_add_f32 v[118:119], v[106:107], v[118:119]
	v_pk_add_f32 v[116:117], v[104:105], v[116:117]
	v_cvt_pk_bf16_f32 v112, v112, v113
	v_cvt_pk_bf16_f32 v113, v114, v115
	v_cvt_pk_bf16_f32 v114, v116, v117
	v_cvt_pk_bf16_f32 v115, v118, v119
	global_store_dwordx4 v[196:197], v[112:115], off
	v_lshlrev_b32_e32 v116, 16, v146
	v_and_b32_e32 v117, 0xffff0000, v146
	v_lshlrev_b32_e32 v112, 16, v144
	v_and_b32_e32 v113, 0xffff0000, v144
	v_lshlrev_b32_e32 v114, 16, v145
	v_and_b32_e32 v115, 0xffff0000, v145
	v_lshlrev_b32_e32 v118, 16, v147
	v_and_b32_e32 v119, 0xffff0000, v147
	v_pk_add_f32 v[114:115], v[102:103], v[114:115]
	v_pk_add_f32 v[112:113], v[100:101], v[112:113]
	v_pk_add_f32 v[118:119], v[98:99], v[118:119]
	v_pk_add_f32 v[116:117], v[96:97], v[116:117]
	v_cvt_pk_bf16_f32 v112, v112, v113
	v_cvt_pk_bf16_f32 v113, v114, v115
	v_cvt_pk_bf16_f32 v114, v116, v117
	v_cvt_pk_bf16_f32 v115, v118, v119
	global_store_dwordx4 v[196:197], v[112:115], off offset:256
	s_nop 1
	v_cndmask_b32_e64 v112, 0, 1, s[52:53]
	v_cmp_ne_u32_e64 s[60:61], 1, v112
	s_cbranch_execz .LBB0_1199

; #define GAS __attribute__((address_space(1)))
; __device__ __forceinline__ float bf_lo(unsigned u) { return __uint_as_float(u << 16); }
; __device__ __forceinline__ float bf_hi(unsigned u) { return __uint_as_float(u & 0xffff0000u); }
; __device__ __forceinline__ v4u pack8(const f32x4 a, const f32x4 b) { v4u w; w.x = cvt_pk_bf16(a[0], a[1]); w.y = cvt_pk_bf16(a[2], a[3]); w.z = cvt_pk_bf16(b[0], b[1]); w.w = cvt_pk_bf16(b[2], b[3]); return w; }
;     __device__ __forceinline__ void operator()(Acc& acc, const Unit& u, int wr, int wc, int fr, int fq, LAS unsigned char* lds) const {
;     ...
;                 } else {
; #pragma unroll
;                     for (int bj = 0; bj < 2; ++bj) { const v4u t = hb[m][bj];
;                         *(GAS v4u*)(HB + (size_t)row * 1024 + c0 + bj * 128) = pack8((f32x4){bf_lo(t.x), bf_hi(t.x), bf_lo(t.y), bf_hi(t.y)} + acc[ai][bj][m][0], (f32x4){bf_lo(t.z), bf_hi(t.z), bf_lo(t.w), bf_hi(t.w)} + acc[ai][bj][m][1]); } } }
.LBB0_1214:
	s_waitcnt vmcnt(6)
	v_lshlrev_b32_e32 v96, 16, v140
	v_and_b32_e32 v97, 0xffff0000, v140
	v_lshlrev_b32_e32 v98, 16, v141
	v_and_b32_e32 v99, 0xffff0000, v141
	v_lshlrev_b32_e32 v100, 16, v142
	v_and_b32_e32 v101, 0xffff0000, v142
	v_lshlrev_b32_e32 v102, 16, v143
	v_and_b32_e32 v103, 0xffff0000, v143
	v_pk_add_f32 v[98:99], v[94:95], v[98:99]
	v_pk_add_f32 v[96:97], v[92:93], v[96:97]
	v_pk_add_f32 v[102:103], v[90:91], v[102:103]
	v_pk_add_f32 v[100:101], v[88:89], v[100:101]
	v_cvt_pk_bf16_f32 v96, v96, v97
	v_cvt_pk_bf16_f32 v97, v98, v99
	v_cvt_pk_bf16_f32 v98, v100, v101
	v_cvt_pk_bf16_f32 v99, v102, v103
	global_store_dwordx4 v[192:193], v[96:99], off
	v_lshlrev_b32_e32 v100, 16, v138
	v_and_b32_e32 v101, 0xffff0000, v138
	v_lshlrev_b32_e32 v96, 16, v136
	v_and_b32_e32 v97, 0xffff0000, v136
	v_lshlrev_b32_e32 v98, 16, v137
	v_and_b32_e32 v99, 0xffff0000, v137
	v_lshlrev_b32_e32 v102, 16, v139
	v_and_b32_e32 v103, 0xffff0000, v139
	v_pk_add_f32 v[98:99], v[86:87], v[98:99]
	v_pk_add_f32 v[96:97], v[84:85], v[96:97]
	v_pk_add_f32 v[102:103], v[82:83], v[102:103]
	v_pk_add_f32 v[100:101], v[80:81], v[100:101]
	v_cvt_pk_bf16_f32 v96, v96, v97
	v_cvt_pk_bf16_f32 v97, v98, v99
	v_cvt_pk_bf16_f32 v98, v100, v101
	v_cvt_pk_bf16_f32 v99, v102, v103
	global_store_dwordx4 v[192:193], v[96:99], off offset:256
	s_cbranch_execz .LBB0_1205

; #define GAS __attribute__((address_space(1)))
; __device__ __forceinline__ float bf_lo(unsigned u) { return __uint_as_float(u << 16); }
; __device__ __forceinline__ float bf_hi(unsigned u) { return __uint_as_float(u & 0xffff0000u); }
; __device__ __forceinline__ v4u pack8(const f32x4 a, const f32x4 b) { v4u w; w.x = cvt_pk_bf16(a[0], a[1]); w.y = cvt_pk_bf16(a[2], a[3]); w.z = cvt_pk_bf16(b[0], b[1]); w.w = cvt_pk_bf16(b[2], b[3]); return w; }
;     __device__ __forceinline__ void operator()(Acc& acc, const Unit& u, int wr, int wc, int fr, int fq, LAS unsigned char* lds) const {
;     ...
;                 } else {
; #pragma unroll
;                     for (int bj = 0; bj < 2; ++bj) { const v4u t = hb[m][bj];
;                         *(GAS v4u*)(HB + (size_t)row * 1024 + c0 + bj * 128) = pack8((f32x4){bf_lo(t.x), bf_hi(t.x), bf_lo(t.y), bf_hi(t.y)} + acc[ai][bj][m][0], (f32x4){bf_lo(t.z), bf_hi(t.z), bf_lo(t.w), bf_hi(t.w)} + acc[ai][bj][m][1]); } } }
.LBB0_1216:
	s_waitcnt vmcnt(6)
	v_lshlrev_b32_e32 v80, 16, v132
	v_and_b32_e32 v81, 0xffff0000, v132
	v_lshlrev_b32_e32 v82, 16, v133
	v_and_b32_e32 v83, 0xffff0000, v133
	v_lshlrev_b32_e32 v84, 16, v134
	v_and_b32_e32 v85, 0xffff0000, v134
	v_lshlrev_b32_e32 v86, 16, v135
	v_and_b32_e32 v87, 0xffff0000, v135
	v_pk_add_f32 v[82:83], v[78:79], v[82:83]
	v_pk_add_f32 v[80:81], v[76:77], v[80:81]
	v_pk_add_f32 v[86:87], v[74:75], v[86:87]
	v_pk_add_f32 v[84:85], v[72:73], v[84:85]
	v_cvt_pk_bf16_f32 v80, v80, v81
	v_cvt_pk_bf16_f32 v81, v82, v83
	v_cvt_pk_bf16_f32 v82, v84, v85
	v_cvt_pk_bf16_f32 v83, v86, v87
	global_store_dwordx4 v[188:189], v[80:83], off
	v_lshlrev_b32_e32 v84, 16, v130
	v_and_b32_e32 v85, 0xffff0000, v130
	v_lshlrev_b32_e32 v80, 16, v128
	v_and_b32_e32 v81, 0xffff0000, v128
	v_lshlrev_b32_e32 v82, 16, v129
	v_and_b32_e32 v83, 0xffff0000, v129
	v_lshlrev_b32_e32 v86, 16, v131
	v_and_b32_e32 v87, 0xffff0000, v131
	v_pk_add_f32 v[82:83], v[70:71], v[82:83]
	v_pk_add_f32 v[80:81], v[68:69], v[80:81]
	v_pk_add_f32 v[86:87], v[66:67], v[86:87]
	v_pk_add_f32 v[84:85], v[64:65], v[84:85]
	v_cvt_pk_bf16_f32 v80, v80, v81
	v_cvt_pk_bf16_f32 v81, v82, v83
	v_cvt_pk_bf16_f32 v82, v84, v85
	v_cvt_pk_bf16_f32 v83, v86, v87
	global_store_dwordx4 v[188:189], v[80:83], off offset:256
	s_cbranch_execnz .LBB0_1222

; #define GAS __attribute__((address_space(1)))
; __device__ __forceinline__ float bf_lo(unsigned u) { return __uint_as_float(u << 16); }
; __device__ __forceinline__ float bf_hi(unsigned u) { return __uint_as_float(u & 0xffff0000u); }
;     __device__ __forceinline__ void operator()(Acc& acc, const Unit& u, int wr, int wc, int fr, int fq, LAS unsigned char* lds) const {
;     ...
;                 if (last) { GAS float* dp; bool ok = true;
;                     if (sample) dp = out + O_YS + (size_t)(row - MPAD) * 1024 + c0;
;                     else { const int b = row / LP, t = row - b * LP; ok = row < MP && t >= NMETA; dp = out + O_YP + ((size_t)b * SEQ + (t - NMETA)) * 1024 + c0; }
;                     if (ok) {
; #pragma unroll
;                         for (int bj = 0; bj < 2; ++bj) { const v4u t = hb[m][bj];
;                             *(GAS f32x4*)(dp + bj * 128) = (f32x4){bf_lo(t.x), bf_hi(t.x), bf_lo(t.y), bf_hi(t.y)} + acc[ai][bj][m][0]; *(GAS f32x4*)(dp + bj * 128 + 4) = (f32x4){bf_lo(t.z), bf_hi(t.z), bf_lo(t.w), bf_hi(t.w)} + acc[ai][bj][m][1]; } }
.LBB0_1220:
	v_ashrrev_i32_e32 v81, 31, v80
	v_lshl_add_u64 v[82:83], s[8:9], 0, v[82:83]
	v_lshlrev_b64 v[80:81], 12, v[80:81]
	v_lshl_add_u64 v[80:81], v[82:83], 0, v[80:81]
	s_cmp_eq_u32 s98, 7
	s_cbranch_scc1 .Leo_f3
	s_waitcnt vmcnt(0)
	s_branch .Leo_j3
.Leo_f3:
	s_waitcnt vmcnt(12)
.Leo_j3:
	v_lshlrev_b32_e32 v82, 16, v132
	v_and_b32_e32 v83, 0xffff0000, v132
	v_lshlrev_b32_e32 v84, 16, v133
	v_and_b32_e32 v85, 0xffff0000, v133
	v_lshl_add_u64 v[80:81], v[170:171], 2, v[80:81]
	v_pk_add_f32 v[78:79], v[78:79], v[84:85]
	v_pk_add_f32 v[76:77], v[76:77], v[82:83]
	global_store_dwordx4 v[80:81], v[76:79], off
	s_nop 1
	v_lshlrev_b32_e32 v76, 16, v134
	v_and_b32_e32 v77, 0xffff0000, v134
	v_lshlrev_b32_e32 v78, 16, v135
	v_and_b32_e32 v79, 0xffff0000, v135
	v_pk_add_f32 v[74:75], v[74:75], v[78:79]
	v_pk_add_f32 v[72:73], v[72:73], v[76:77]
	global_store_dwordx4 v[80:81], v[72:75], off offset:16
	s_nop 1
	v_lshlrev_b32_e32 v72, 16, v128
	v_and_b32_e32 v73, 0xffff0000, v128
	v_lshlrev_b32_e32 v74, 16, v129
	v_and_b32_e32 v75, 0xffff0000, v129
	v_pk_add_f32 v[70:71], v[70:71], v[74:75]
	v_pk_add_f32 v[68:69], v[68:69], v[72:73]
	global_store_dwordx4 v[80:81], v[68:71], off offset:512
	s_nop 1
	v_lshlrev_b32_e32 v68, 16, v130
	v_and_b32_e32 v69, 0xffff0000, v130
	v_lshlrev_b32_e32 v70, 16, v131
	v_and_b32_e32 v71, 0xffff0000, v131
	v_pk_add_f32 v[66:67], v[66:67], v[70:71]
	v_pk_add_f32 v[64:65], v[64:65], v[68:69]
	global_store_dwordx4 v[80:81], v[64:67], off offset:528

; #define GAS __attribute__((address_space(1)))
; __device__ __forceinline__ float bf_lo(unsigned u) { return __uint_as_float(u << 16); }
; __device__ __forceinline__ float bf_hi(unsigned u) { return __uint_as_float(u & 0xffff0000u); }
; __device__ __forceinline__ v4u pack8(const f32x4 a, const f32x4 b) { v4u w; w.x = cvt_pk_bf16(a[0], a[1]); w.y = cvt_pk_bf16(a[2], a[3]); w.z = cvt_pk_bf16(b[0], b[1]); w.w = cvt_pk_bf16(b[2], b[3]); return w; }
;     __device__ __forceinline__ void operator()(Acc& acc, const Unit& u, int wr, int wc, int fr, int fq, LAS unsigned char* lds) const {
;     ...
;         for (int ai = 0; ai < 2; ++ai) {
;             v4u hb[4][2];
; #pragma unroll
;             for (int m = 0; m < 4; ++m)
; #pragma unroll
;                 for (int bj = 0; bj < 2; ++bj) hb[m][bj] = *(const GAS v4u*)(HB + (size_t)(row0 + ai * 128 + m * 16) * 1024 + c0 + bj * 128);
; #pragma unroll
;             for (int m = 0; m < 4; ++m) { const int row = row0 + ai * 128 + m * 16;
;                 if (last) { GAS float* dp; bool ok = true;
;                     if (sample) dp = out + O_YS + (size_t)(row - MPAD) * 1024 + c0;
;                     else { const int b = row / LP, t = row - b * LP; ok = row < MP && t >= NMETA; dp = out + O_YP + ((size_t)b * SEQ + (t - NMETA)) * 1024 + c0; }
;                     if (ok) {
; #pragma unroll
;                         for (int bj = 0; bj < 2; ++bj) { const v4u t = hb[m][bj];
;                             *(GAS f32x4*)(dp + bj * 128) = (f32x4){bf_lo(t.x), bf_hi(t.x), bf_lo(t.y), bf_hi(t.y)} + acc[ai][bj][m][0]; *(GAS f32x4*)(dp + bj * 128 + 4) = (f32x4){bf_lo(t.z), bf_hi(t.z), bf_lo(t.w), bf_hi(t.w)} + acc[ai][bj][m][1]; } }
;                 } else {
; #pragma unroll
;                     for (int bj = 0; bj < 2; ++bj) { const v4u t = hb[m][bj];
;                         *(GAS v4u*)(HB + (size_t)row * 1024 + c0 + bj * 128) = pack8((f32x4){bf_lo(t.x), bf_hi(t.x), bf_lo(t.y), bf_hi(t.y)} + acc[ai][bj][m][0], (f32x4){bf_lo(t.z), bf_hi(t.z), bf_lo(t.w), bf_hi(t.w)} + acc[ai][bj][m][1]); } } }
.LBB0_1222:
	v_add_u32_e32 v108, 0x80, v182
	v_ashrrev_i32_e32 v109, 31, v108
	v_add_u32_e32 v104, 0x90, v182
	v_lshlrev_b64 v[64:65], 11, v[108:109]
	v_ashrrev_i32_e32 v105, 31, v104
	v_add_u32_e32 v100, 0xa0, v182
	v_lshl_add_u64 v[110:111], v[184:185], 0, v[64:65]
	v_lshlrev_b64 v[64:65], 11, v[104:105]
	v_ashrrev_i32_e32 v101, 31, v100
	v_add_u32_e32 v96, 0xb0, v182
	v_lshl_add_u64 v[106:107], v[184:185], 0, v[64:65]
	v_lshlrev_b64 v[64:65], 11, v[100:101]
	v_ashrrev_i32_e32 v97, 31, v96
	v_lshl_add_u64 v[102:103], v[184:185], 0, v[64:65]
	v_lshlrev_b64 v[64:65], 11, v[96:97]
	v_lshl_add_u64 v[98:99], v[184:185], 0, v[64:65]
	s_mov_b32 s98, 0
	global_load_dwordx4 v[92:95], v[110:111], off
	global_load_dwordx4 v[88:91], v[110:111], off offset:256
	global_load_dwordx4 v[84:87], v[106:107], off
	global_load_dwordx4 v[80:83], v[106:107], off offset:256
	global_load_dwordx4 v[76:79], v[102:103], off
	global_load_dwordx4 v[72:75], v[102:103], off offset:256
	global_load_dwordx4 v[68:71], v[98:99], off
	global_load_dwordx4 v[64:67], v[98:99], off offset:256
	s_mov_b64 s[52:53], -1
	s_and_b64 vcc, exec, s[34:35]
	s_cbranch_vccz .LBB0_1231
	s_waitcnt vmcnt(6)
	v_lshlrev_b32_e32 v112, 16, v92
	v_and_b32_e32 v113, 0xffff0000, v92
	v_lshlrev_b32_e32 v114, 16, v93
	v_and_b32_e32 v115, 0xffff0000, v93
	v_lshlrev_b32_e32 v116, 16, v94
	v_and_b32_e32 v117, 0xffff0000, v94
	v_lshlrev_b32_e32 v118, 16, v95
	v_and_b32_e32 v119, 0xffff0000, v95
	v_pk_add_f32 v[114:115], v[62:63], v[114:115]
	v_pk_add_f32 v[112:113], v[60:61], v[112:113]
	v_pk_add_f32 v[118:119], v[58:59], v[118:119]
	v_pk_add_f32 v[116:117], v[56:57], v[116:117]
	v_cvt_pk_bf16_f32 v112, v112, v113
	v_cvt_pk_bf16_f32 v113, v114, v115
	v_cvt_pk_bf16_f32 v114, v116, v117
	v_cvt_pk_bf16_f32 v115, v118, v119
	global_store_dwordx4 v[110:111], v[112:115], off
	v_lshlrev_b32_e32 v116, 16, v90
	v_and_b32_e32 v117, 0xffff0000, v90
	v_lshlrev_b32_e32 v112, 16, v88
	v_and_b32_e32 v113, 0xffff0000, v88
	v_lshlrev_b32_e32 v114, 16, v89
	v_and_b32_e32 v115, 0xffff0000, v89
	v_lshlrev_b32_e32 v118, 16, v91
	v_and_b32_e32 v119, 0xffff0000, v91
	v_pk_add_f32 v[114:115], v[54:55], v[114:115]
	v_pk_add_f32 v[112:113], v[52:53], v[112:113]
	v_pk_add_f32 v[118:119], v[50:51], v[118:119]
	v_pk_add_f32 v[116:117], v[48:49], v[116:117]
	v_cvt_pk_bf16_f32 v112, v112, v113
	v_cvt_pk_bf16_f32 v113, v114, v115
	v_cvt_pk_bf16_f32 v114, v116, v117
	v_cvt_pk_bf16_f32 v115, v118, v119
	global_store_dwordx4 v[110:111], v[112:115], off offset:256
	s_cbranch_execz .LBB0_1232

; #define GAS __attribute__((address_space(1)))
; __device__ __forceinline__ float bf_lo(unsigned u) { return __uint_as_float(u << 16); }
; __device__ __forceinline__ float bf_hi(unsigned u) { return __uint_as_float(u & 0xffff0000u); }
; __device__ __forceinline__ v4u pack8(const f32x4 a, const f32x4 b) { v4u w; w.x = cvt_pk_bf16(a[0], a[1]); w.y = cvt_pk_bf16(a[2], a[3]); w.z = cvt_pk_bf16(b[0], b[1]); w.w = cvt_pk_bf16(b[2], b[3]); return w; }
;     __device__ __forceinline__ void operator()(Acc& acc, const Unit& u, int wr, int wc, int fr, int fq, LAS unsigned char* lds) const {
;     ...
;                 } else {
; #pragma unroll
;                     for (int bj = 0; bj < 2; ++bj) { const v4u t = hb[m][bj];
;                         *(GAS v4u*)(HB + (size_t)row * 1024 + c0 + bj * 128) = pack8((f32x4){bf_lo(t.x), bf_hi(t.x), bf_lo(t.y), bf_hi(t.y)} + acc[ai][bj][m][0], (f32x4){bf_lo(t.z), bf_hi(t.z), bf_lo(t.w), bf_hi(t.w)} + acc[ai][bj][m][1]); } } }
.LBB0_1225:
	s_waitcnt vmcnt(6)
	v_lshlrev_b32_e32 v48, 16, v84
	v_and_b32_e32 v49, 0xffff0000, v84
	v_lshlrev_b32_e32 v50, 16, v85
	v_and_b32_e32 v51, 0xffff0000, v85
	v_lshlrev_b32_e32 v52, 16, v86
	v_and_b32_e32 v53, 0xffff0000, v86
	v_lshlrev_b32_e32 v54, 16, v87
	v_and_b32_e32 v55, 0xffff0000, v87
	v_pk_add_f32 v[50:51], v[46:47], v[50:51]
	v_pk_add_f32 v[48:49], v[44:45], v[48:49]
	v_pk_add_f32 v[54:55], v[42:43], v[54:55]
	v_pk_add_f32 v[52:53], v[40:41], v[52:53]
	v_cvt_pk_bf16_f32 v48, v48, v49
	v_cvt_pk_bf16_f32 v49, v50, v51
	v_cvt_pk_bf16_f32 v50, v52, v53
	v_cvt_pk_bf16_f32 v51, v54, v55
	global_store_dwordx4 v[106:107], v[48:51], off
	v_lshlrev_b32_e32 v52, 16, v82
	v_and_b32_e32 v53, 0xffff0000, v82
	v_lshlrev_b32_e32 v48, 16, v80
	v_and_b32_e32 v49, 0xffff0000, v80
	v_lshlrev_b32_e32 v50, 16, v81
	v_and_b32_e32 v51, 0xffff0000, v81
	v_lshlrev_b32_e32 v54, 16, v83
	v_and_b32_e32 v55, 0xffff0000, v83
	v_pk_add_f32 v[50:51], v[38:39], v[50:51]
	v_pk_add_f32 v[48:49], v[36:37], v[48:49]
	v_pk_add_f32 v[54:55], v[34:35], v[54:55]
	v_pk_add_f32 v[52:53], v[32:33], v[52:53]
	v_cvt_pk_bf16_f32 v48, v48, v49
	v_cvt_pk_bf16_f32 v49, v50, v51
	v_cvt_pk_bf16_f32 v50, v52, v53
	v_cvt_pk_bf16_f32 v51, v54, v55
	global_store_dwordx4 v[106:107], v[48:51], off offset:256
	s_cbranch_execz .LBB0_1238

; #define GAS __attribute__((address_space(1)))
; __device__ __forceinline__ float bf_lo(unsigned u) { return __uint_as_float(u << 16); }
; __device__ __forceinline__ float bf_hi(unsigned u) { return __uint_as_float(u & 0xffff0000u); }
; __device__ __forceinline__ v4u pack8(const f32x4 a, const f32x4 b) { v4u w; w.x = cvt_pk_bf16(a[0], a[1]); w.y = cvt_pk_bf16(a[2], a[3]); w.z = cvt_pk_bf16(b[0], b[1]); w.w = cvt_pk_bf16(b[2], b[3]); return w; }
;     __device__ __forceinline__ void operator()(Acc& acc, const Unit& u, int wr, int wc, int fr, int fq, LAS unsigned char* lds) const {
;     ...
;                 } else {
; #pragma unroll
;                     for (int bj = 0; bj < 2; ++bj) { const v4u t = hb[m][bj];
;                         *(GAS v4u*)(HB + (size_t)row * 1024 + c0 + bj * 128) = pack8((f32x4){bf_lo(t.x), bf_hi(t.x), bf_lo(t.y), bf_hi(t.y)} + acc[ai][bj][m][0], (f32x4){bf_lo(t.z), bf_hi(t.z), bf_lo(t.w), bf_hi(t.w)} + acc[ai][bj][m][1]); } } }
.LBB0_1227:
	s_waitcnt vmcnt(6)
	v_lshlrev_b32_e32 v32, 16, v76
	v_and_b32_e32 v33, 0xffff0000, v76
	v_lshlrev_b32_e32 v34, 16, v77
	v_and_b32_e32 v35, 0xffff0000, v77
	v_lshlrev_b32_e32 v36, 16, v78
	v_and_b32_e32 v37, 0xffff0000, v78
	v_lshlrev_b32_e32 v38, 16, v79
	v_and_b32_e32 v39, 0xffff0000, v79
	v_pk_add_f32 v[34:35], v[30:31], v[34:35]
	v_pk_add_f32 v[32:33], v[28:29], v[32:33]
	v_pk_add_f32 v[38:39], v[26:27], v[38:39]
	v_pk_add_f32 v[36:37], v[24:25], v[36:37]
	v_cvt_pk_bf16_f32 v32, v32, v33
	v_cvt_pk_bf16_f32 v33, v34, v35
	v_cvt_pk_bf16_f32 v34, v36, v37
	v_cvt_pk_bf16_f32 v35, v38, v39
	global_store_dwordx4 v[102:103], v[32:35], off
	v_lshlrev_b32_e32 v36, 16, v74
	v_and_b32_e32 v37, 0xffff0000, v74
	v_lshlrev_b32_e32 v32, 16, v72
	v_and_b32_e32 v33, 0xffff0000, v72
	v_lshlrev_b32_e32 v34, 16, v73
	v_and_b32_e32 v35, 0xffff0000, v73
	v_lshlrev_b32_e32 v38, 16, v75
	v_and_b32_e32 v39, 0xffff0000, v75
	v_pk_add_f32 v[34:35], v[22:23], v[34:35]
	v_pk_add_f32 v[32:33], v[20:21], v[32:33]
	v_pk_add_f32 v[38:39], v[18:19], v[38:39]
	v_pk_add_f32 v[36:37], v[16:17], v[36:37]
	v_cvt_pk_bf16_f32 v32, v32, v33
	v_cvt_pk_bf16_f32 v33, v34, v35
	v_cvt_pk_bf16_f32 v34, v36, v37
	v_cvt_pk_bf16_f32 v35, v38, v39
	global_store_dwordx4 v[102:103], v[32:35], off offset:256
	s_cbranch_execz .LBB0_1244

; #define GAS __attribute__((address_space(1)))
; __device__ __forceinline__ float bf_lo(unsigned u) { return __uint_as_float(u << 16); }
; __device__ __forceinline__ float bf_hi(unsigned u) { return __uint_as_float(u & 0xffff0000u); }
; __device__ __forceinline__ v4u pack8(const f32x4 a, const f32x4 b) { v4u w; w.x = cvt_pk_bf16(a[0], a[1]); w.y = cvt_pk_bf16(a[2], a[3]); w.z = cvt_pk_bf16(b[0], b[1]); w.w = cvt_pk_bf16(b[2], b[3]); return w; }
;     __device__ __forceinline__ void operator()(Acc& acc, const Unit& u, int wr, int wc, int fr, int fq, LAS unsigned char* lds) const {
;     ...
;                 } else {
; #pragma unroll
;                     for (int bj = 0; bj < 2; ++bj) { const v4u t = hb[m][bj];
;                         *(GAS v4u*)(HB + (size_t)row * 1024 + c0 + bj * 128) = pack8((f32x4){bf_lo(t.x), bf_hi(t.x), bf_lo(t.y), bf_hi(t.y)} + acc[ai][bj][m][0], (f32x4){bf_lo(t.z), bf_hi(t.z), bf_lo(t.w), bf_hi(t.w)} + acc[ai][bj][m][1]); } } }
.LBB0_1229:
	s_waitcnt vmcnt(6)
	v_lshlrev_b32_e32 v16, 16, v68
	v_and_b32_e32 v17, 0xffff0000, v68
	v_lshlrev_b32_e32 v18, 16, v69
	v_and_b32_e32 v19, 0xffff0000, v69
	v_lshlrev_b32_e32 v20, 16, v70
	v_and_b32_e32 v21, 0xffff0000, v70
	v_lshlrev_b32_e32 v22, 16, v71
	v_and_b32_e32 v23, 0xffff0000, v71
	v_pk_add_f32 v[18:19], v[14:15], v[18:19]
	v_pk_add_f32 v[16:17], v[12:13], v[16:17]
	v_pk_add_f32 v[22:23], v[10:11], v[22:23]
	v_pk_add_f32 v[20:21], v[8:9], v[20:21]
	v_cvt_pk_bf16_f32 v16, v16, v17
	v_cvt_pk_bf16_f32 v17, v18, v19
	v_cvt_pk_bf16_f32 v18, v20, v21
	v_cvt_pk_bf16_f32 v19, v22, v23
	global_store_dwordx4 v[98:99], v[16:19], off
	v_lshlrev_b32_e32 v20, 16, v66
	v_and_b32_e32 v21, 0xffff0000, v66
	v_lshlrev_b32_e32 v16, 16, v64
	v_and_b32_e32 v17, 0xffff0000, v64
	v_lshlrev_b32_e32 v18, 16, v65
	v_and_b32_e32 v19, 0xffff0000, v65
	v_lshlrev_b32_e32 v22, 16, v67
	v_and_b32_e32 v23, 0xffff0000, v67
	v_pk_add_f32 v[18:19], v[6:7], v[18:19]
	v_pk_add_f32 v[16:17], v[4:5], v[16:17]
	v_pk_add_f32 v[22:23], v[2:3], v[22:23]
	v_pk_add_f32 v[20:21], v[0:1], v[20:21]
	v_cvt_pk_bf16_f32 v16, v16, v17
	v_cvt_pk_bf16_f32 v17, v18, v19
	v_cvt_pk_bf16_f32 v18, v20, v21
	v_cvt_pk_bf16_f32 v19, v22, v23
	global_store_dwordx4 v[98:99], v[16:19], off offset:256
	s_cbranch_execz .LBB0_1250

; #define GAS __attribute__((address_space(1)))
; __device__ __forceinline__ float bf_lo(unsigned u) { return __uint_as_float(u << 16); }
; __device__ __forceinline__ float bf_hi(unsigned u) { return __uint_as_float(u & 0xffff0000u); }
;     __device__ __forceinline__ void operator()(Acc& acc, const Unit& u, int wr, int wc, int fr, int fq, LAS unsigned char* lds) const {
;     ...
;                 if (last) { GAS float* dp; bool ok = true;
;                     if (sample) dp = out + O_YS + (size_t)(row - MPAD) * 1024 + c0;
;                     else { const int b = row / LP, t = row - b * LP; ok = row < MP && t >= NMETA; dp = out + O_YP + ((size_t)b * SEQ + (t - NMETA)) * 1024 + c0; }
;                     if (ok) {
; #pragma unroll
;                         for (int bj = 0; bj < 2; ++bj) { const v4u t = hb[m][bj];
;                             *(GAS f32x4*)(dp + bj * 128) = (f32x4){bf_lo(t.x), bf_hi(t.x), bf_lo(t.y), bf_hi(t.y)} + acc[ai][bj][m][0]; *(GAS f32x4*)(dp + bj * 128 + 4) = (f32x4){bf_lo(t.z), bf_hi(t.z), bf_lo(t.w), bf_hi(t.w)} + acc[ai][bj][m][1]; } }
.LBB0_1235:
	v_ashrrev_i32_e32 v111, 31, v110
	v_lshl_add_u64 v[108:109], s[8:9], 0, v[112:113]
	v_lshlrev_b64 v[110:111], 12, v[110:111]
	v_lshl_add_u64 v[108:109], v[108:109], 0, v[110:111]
	s_waitcnt vmcnt(6)
	v_lshlrev_b32_e32 v110, 16, v92
	v_and_b32_e32 v111, 0xffff0000, v92
	v_lshlrev_b32_e32 v92, 16, v93
	v_and_b32_e32 v93, 0xffff0000, v93
	v_lshl_add_u64 v[108:109], v[170:171], 2, v[108:109]
	v_pk_add_f32 v[62:63], v[62:63], v[92:93]
	v_pk_add_f32 v[60:61], v[60:61], v[110:111]
	global_store_dwordx4 v[108:109], v[60:63], off
	s_nop 1
	v_lshlrev_b32_e32 v60, 16, v94
	v_and_b32_e32 v61, 0xffff0000, v94
	v_lshlrev_b32_e32 v62, 16, v95
	v_and_b32_e32 v63, 0xffff0000, v95
	v_pk_add_f32 v[58:59], v[58:59], v[62:63]
	v_pk_add_f32 v[56:57], v[56:57], v[60:61]
	global_store_dwordx4 v[108:109], v[56:59], off offset:16
	s_nop 1
	v_lshlrev_b32_e32 v56, 16, v88
	v_and_b32_e32 v57, 0xffff0000, v88
	v_lshlrev_b32_e32 v58, 16, v89
	v_and_b32_e32 v59, 0xffff0000, v89
	v_pk_add_f32 v[54:55], v[54:55], v[58:59]
	v_pk_add_f32 v[52:53], v[52:53], v[56:57]
	global_store_dwordx4 v[108:109], v[52:55], off offset:512
	s_nop 1
	v_lshlrev_b32_e32 v52, 16, v90
	v_and_b32_e32 v53, 0xffff0000, v90
	v_lshlrev_b32_e32 v54, 16, v91
	v_and_b32_e32 v55, 0xffff0000, v91
	v_pk_add_f32 v[50:51], v[50:51], v[54:55]
	v_pk_add_f32 v[48:49], v[48:49], v[52:53]
	global_store_dwordx4 v[108:109], v[48:51], off offset:528
	s_bitset1_b32 s98, 0

; #define GAS __attribute__((address_space(1)))
; __device__ __forceinline__ float bf_lo(unsigned u) { return __uint_as_float(u << 16); }
; __device__ __forceinline__ float bf_hi(unsigned u) { return __uint_as_float(u & 0xffff0000u); }
;     __device__ __forceinline__ void operator()(Acc& acc, const Unit& u, int wr, int wc, int fr, int fq, LAS unsigned char* lds) const {
;     ...
;                 if (last) { GAS float* dp; bool ok = true;
;                     if (sample) dp = out + O_YS + (size_t)(row - MPAD) * 1024 + c0;
;                     else { const int b = row / LP, t = row - b * LP; ok = row < MP && t >= NMETA; dp = out + O_YP + ((size_t)b * SEQ + (t - NMETA)) * 1024 + c0; }
;                     if (ok) {
; #pragma unroll
;                         for (int bj = 0; bj < 2; ++bj) { const v4u t = hb[m][bj];
;                             *(GAS f32x4*)(dp + bj * 128) = (f32x4){bf_lo(t.x), bf_hi(t.x), bf_lo(t.y), bf_hi(t.y)} + acc[ai][bj][m][0]; *(GAS f32x4*)(dp + bj * 128 + 4) = (f32x4){bf_lo(t.z), bf_hi(t.z), bf_lo(t.w), bf_hi(t.w)} + acc[ai][bj][m][1]; } }
.LBB0_1241:
	v_ashrrev_i32_e32 v49, 31, v48
	v_lshl_add_u64 v[50:51], s[8:9], 0, v[50:51]
	v_lshlrev_b64 v[48:49], 12, v[48:49]
	v_lshl_add_u64 v[48:49], v[50:51], 0, v[48:49]
	s_cmp_eq_u32 s98, 1
	s_cbranch_scc1 .Leo_f5
	s_waitcnt vmcnt(4)
	s_branch .Leo_j5

; #define GAS __attribute__((address_space(1)))
; __device__ __forceinline__ float bf_lo(unsigned u) { return __uint_as_float(u << 16); }
; __device__ __forceinline__ float bf_hi(unsigned u) { return __uint_as_float(u & 0xffff0000u); }
;     __device__ __forceinline__ void operator()(Acc& acc, const Unit& u, int wr, int wc, int fr, int fq, LAS unsigned char* lds) const {
;     ...
;                 if (last) { GAS float* dp; bool ok = true;
;                     if (sample) dp = out + O_YS + (size_t)(row - MPAD) * 1024 + c0;
;                     else { const int b = row / LP, t = row - b * LP; ok = row < MP && t >= NMETA; dp = out + O_YP + ((size_t)b * SEQ + (t - NMETA)) * 1024 + c0; }
;                     if (ok) {
; #pragma unroll
;                         for (int bj = 0; bj < 2; ++bj) { const v4u t = hb[m][bj];
;                             *(GAS f32x4*)(dp + bj * 128) = (f32x4){bf_lo(t.x), bf_hi(t.x), bf_lo(t.y), bf_hi(t.y)} + acc[ai][bj][m][0]; *(GAS f32x4*)(dp + bj * 128 + 4) = (f32x4){bf_lo(t.z), bf_hi(t.z), bf_lo(t.w), bf_hi(t.w)} + acc[ai][bj][m][1]; } }
.Leo_j5:
	v_lshlrev_b32_e32 v50, 16, v84
	v_and_b32_e32 v51, 0xffff0000, v84
	v_lshlrev_b32_e32 v52, 16, v85
	v_and_b32_e32 v53, 0xffff0000, v85
	v_lshl_add_u64 v[48:49], v[170:171], 2, v[48:49]
	v_pk_add_f32 v[46:47], v[46:47], v[52:53]
	v_pk_add_f32 v[44:45], v[44:45], v[50:51]
	global_store_dwordx4 v[48:49], v[44:47], off
	s_nop 1
	v_lshlrev_b32_e32 v44, 16, v86
	v_and_b32_e32 v45, 0xffff0000, v86
	v_lshlrev_b32_e32 v46, 16, v87
	v_and_b32_e32 v47, 0xffff0000, v87
	v_pk_add_f32 v[42:43], v[42:43], v[46:47]
	v_pk_add_f32 v[40:41], v[40:41], v[44:45]
	global_store_dwordx4 v[48:49], v[40:43], off offset:16
	s_nop 1
	v_lshlrev_b32_e32 v40, 16, v80
	v_and_b32_e32 v41, 0xffff0000, v80
	v_lshlrev_b32_e32 v42, 16, v81
	v_and_b32_e32 v43, 0xffff0000, v81
	v_pk_add_f32 v[38:39], v[38:39], v[42:43]
	v_pk_add_f32 v[36:37], v[36:37], v[40:41]
	global_store_dwordx4 v[48:49], v[36:39], off offset:512
	s_nop 1
	v_lshlrev_b32_e32 v36, 16, v82
	v_and_b32_e32 v37, 0xffff0000, v82
	v_lshlrev_b32_e32 v38, 16, v83
	v_and_b32_e32 v39, 0xffff0000, v83
	v_pk_add_f32 v[34:35], v[34:35], v[38:39]
	v_pk_add_f32 v[32:33], v[32:33], v[36:37]
	global_store_dwordx4 v[48:49], v[32:35], off offset:528
	s_bitset1_b32 s98, 1

; #define GAS __attribute__((address_space(1)))
; __device__ __forceinline__ float bf_lo(unsigned u) { return __uint_as_float(u << 16); }
; __device__ __forceinline__ float bf_hi(unsigned u) { return __uint_as_float(u & 0xffff0000u); }
;     __device__ __forceinline__ void operator()(Acc& acc, const Unit& u, int wr, int wc, int fr, int fq, LAS unsigned char* lds) const {
;     ...
;                 if (last) { GAS float* dp; bool ok = true;
;                     if (sample) dp = out + O_YS + (size_t)(row - MPAD) * 1024 + c0;
;                     else { const int b = row / LP, t = row - b * LP; ok = row < MP && t >= NMETA; dp = out + O_YP + ((size_t)b * SEQ + (t - NMETA)) * 1024 + c0; }
;                     if (ok) {
; #pragma unroll
;                         for (int bj = 0; bj < 2; ++bj) { const v4u t = hb[m][bj];
;                             *(GAS f32x4*)(dp + bj * 128) = (f32x4){bf_lo(t.x), bf_hi(t.x), bf_lo(t.y), bf_hi(t.y)} + acc[ai][bj][m][0]; *(GAS f32x4*)(dp + bj * 128 + 4) = (f32x4){bf_lo(t.z), bf_hi(t.z), bf_lo(t.w), bf_hi(t.w)} + acc[ai][bj][m][1]; } }
.LBB0_1247:
	v_ashrrev_i32_e32 v33, 31, v32
	v_lshl_add_u64 v[34:35], s[8:9], 0, v[34:35]
	v_lshlrev_b64 v[32:33], 12, v[32:33]
	v_lshl_add_u64 v[32:33], v[34:35], 0, v[32:33]
	s_cmp_eq_u32 s98, 3
	s_cbranch_scc1 .Leo_f6
	s_waitcnt vmcnt(2)
	s_branch .Leo_j6

; #define GAS __attribute__((address_space(1)))
; __device__ __forceinline__ float bf_lo(unsigned u) { return __uint_as_float(u << 16); }
; __device__ __forceinline__ float bf_hi(unsigned u) { return __uint_as_float(u & 0xffff0000u); }
;     __device__ __forceinline__ void operator()(Acc& acc, const Unit& u, int wr, int wc, int fr, int fq, LAS unsigned char* lds) const {
;     ...
;                 if (last) { GAS float* dp; bool ok = true;
;                     if (sample) dp = out + O_YS + (size_t)(row - MPAD) * 1024 + c0;
;                     else { const int b = row / LP, t = row - b * LP; ok = row < MP && t >= NMETA; dp = out + O_YP + ((size_t)b * SEQ + (t - NMETA)) * 1024 + c0; }
;                     if (ok) {
; #pragma unroll
;                         for (int bj = 0; bj < 2; ++bj) { const v4u t = hb[m][bj];
;                             *(GAS f32x4*)(dp + bj * 128) = (f32x4){bf_lo(t.x), bf_hi(t.x), bf_lo(t.y), bf_hi(t.y)} + acc[ai][bj][m][0]; *(GAS f32x4*)(dp + bj * 128 + 4) = (f32x4){bf_lo(t.z), bf_hi(t.z), bf_lo(t.w), bf_hi(t.w)} + acc[ai][bj][m][1]; } }
.Leo_j6:
	v_lshlrev_b32_e32 v34, 16, v76
	v_and_b32_e32 v35, 0xffff0000, v76
	v_lshlrev_b32_e32 v36, 16, v77
	v_and_b32_e32 v37, 0xffff0000, v77
	v_lshl_add_u64 v[32:33], v[170:171], 2, v[32:33]
	v_pk_add_f32 v[30:31], v[30:31], v[36:37]
	v_pk_add_f32 v[28:29], v[28:29], v[34:35]
	global_store_dwordx4 v[32:33], v[28:31], off
	s_nop 1
	v_lshlrev_b32_e32 v28, 16, v78
	v_and_b32_e32 v29, 0xffff0000, v78
	v_lshlrev_b32_e32 v30, 16, v79
	v_and_b32_e32 v31, 0xffff0000, v79
	v_pk_add_f32 v[26:27], v[26:27], v[30:31]
	v_pk_add_f32 v[24:25], v[24:25], v[28:29]
	global_store_dwordx4 v[32:33], v[24:27], off offset:16
	s_nop 1
	v_lshlrev_b32_e32 v24, 16, v72
	v_and_b32_e32 v25, 0xffff0000, v72
	v_lshlrev_b32_e32 v26, 16, v73
	v_and_b32_e32 v27, 0xffff0000, v73
	v_pk_add_f32 v[22:23], v[22:23], v[26:27]
	v_pk_add_f32 v[20:21], v[20:21], v[24:25]
	global_store_dwordx4 v[32:33], v[20:23], off offset:512
	s_nop 1
	v_lshlrev_b32_e32 v20, 16, v74
	v_and_b32_e32 v21, 0xffff0000, v74
	v_lshlrev_b32_e32 v22, 16, v75
	v_and_b32_e32 v23, 0xffff0000, v75
	v_pk_add_f32 v[18:19], v[18:19], v[22:23]
	v_pk_add_f32 v[16:17], v[16:17], v[20:21]
	global_store_dwordx4 v[32:33], v[16:19], off offset:528
	s_bitset1_b32 s98, 2

; #define GAS __attribute__((address_space(1)))
; __device__ __forceinline__ float bf_lo(unsigned u) { return __uint_as_float(u << 16); }
; __device__ __forceinline__ float bf_hi(unsigned u) { return __uint_as_float(u & 0xffff0000u); }
;     __device__ __forceinline__ void operator()(Acc& acc, const Unit& u, int wr, int wc, int fr, int fq, LAS unsigned char* lds) const {
;     ...
;                 if (last) { GAS float* dp; bool ok = true;
;                     if (sample) dp = out + O_YS + (size_t)(row - MPAD) * 1024 + c0;
;                     else { const int b = row / LP, t = row - b * LP; ok = row < MP && t >= NMETA; dp = out + O_YP + ((size_t)b * SEQ + (t - NMETA)) * 1024 + c0; }
;                     if (ok) {
; #pragma unroll
;                         for (int bj = 0; bj < 2; ++bj) { const v4u t = hb[m][bj];
;                             *(GAS f32x4*)(dp + bj * 128) = (f32x4){bf_lo(t.x), bf_hi(t.x), bf_lo(t.y), bf_hi(t.y)} + acc[ai][bj][m][0]; *(GAS f32x4*)(dp + bj * 128 + 4) = (f32x4){bf_lo(t.z), bf_hi(t.z), bf_lo(t.w), bf_hi(t.w)} + acc[ai][bj][m][1]; } }
.LBB0_1253:
	v_ashrrev_i32_e32 v17, 31, v16
	v_lshl_add_u64 v[18:19], s[8:9], 0, v[18:19]
	v_lshlrev_b64 v[16:17], 12, v[16:17]
	v_lshl_add_u64 v[16:17], v[18:19], 0, v[16:17]
	s_cmp_eq_u32 s98, 7
	s_cbranch_scc1 .Leo_f7
	s_waitcnt vmcnt(0)
	s_branch .Leo_j7

; #define GAS __attribute__((address_space(1)))
; __device__ __forceinline__ float bf_lo(unsigned u) { return __uint_as_float(u << 16); }
; __device__ __forceinline__ float bf_hi(unsigned u) { return __uint_as_float(u & 0xffff0000u); }
;     __device__ __forceinline__ void operator()(Acc& acc, const Unit& u, int wr, int wc, int fr, int fq, LAS unsigned char* lds) const {
;     ...
;                 if (last) { GAS float* dp; bool ok = true;
;                     if (sample) dp = out + O_YS + (size_t)(row - MPAD) * 1024 + c0;
;                     else { const int b = row / LP, t = row - b * LP; ok = row < MP && t >= NMETA; dp = out + O_YP + ((size_t)b * SEQ + (t - NMETA)) * 1024 + c0; }
;                     if (ok) {
; #pragma unroll
;                         for (int bj = 0; bj < 2; ++bj) { const v4u t = hb[m][bj];
;                             *(GAS f32x4*)(dp + bj * 128) = (f32x4){bf_lo(t.x), bf_hi(t.x), bf_lo(t.y), bf_hi(t.y)} + acc[ai][bj][m][0]; *(GAS f32x4*)(dp + bj * 128 + 4) = (f32x4){bf_lo(t.z), bf_hi(t.z), bf_lo(t.w), bf_hi(t.w)} + acc[ai][bj][m][1]; } }
.Leo_j7:
	v_lshlrev_b32_e32 v18, 16, v68
	v_and_b32_e32 v19, 0xffff0000, v68
	v_lshlrev_b32_e32 v20, 16, v69
	v_and_b32_e32 v21, 0xffff0000, v69
	v_lshl_add_u64 v[16:17], v[170:171], 2, v[16:17]
	v_pk_add_f32 v[14:15], v[14:15], v[20:21]
	v_pk_add_f32 v[12:13], v[12:13], v[18:19]
	global_store_dwordx4 v[16:17], v[12:15], off
	s_nop 1
	v_lshlrev_b32_e32 v12, 16, v70
	v_and_b32_e32 v13, 0xffff0000, v70
	v_lshlrev_b32_e32 v14, 16, v71
	v_and_b32_e32 v15, 0xffff0000, v71
	v_pk_add_f32 v[10:11], v[10:11], v[14:15]
	v_pk_add_f32 v[8:9], v[8:9], v[12:13]
	global_store_dwordx4 v[16:17], v[8:11], off offset:16
	s_nop 1
	v_lshlrev_b32_e32 v8, 16, v64
	v_and_b32_e32 v9, 0xffff0000, v64
	v_lshlrev_b32_e32 v10, 16, v65
	v_and_b32_e32 v11, 0xffff0000, v65
	v_pk_add_f32 v[6:7], v[6:7], v[10:11]
	v_pk_add_f32 v[4:5], v[4:5], v[8:9]
	global_store_dwordx4 v[16:17], v[4:7], off offset:512
	s_nop 1
	v_lshlrev_b32_e32 v4, 16, v66
	v_and_b32_e32 v5, 0xffff0000, v66
	v_lshlrev_b32_e32 v6, 16, v67
	v_and_b32_e32 v7, 0xffff0000, v67
	v_pk_add_f32 v[2:3], v[2:3], v[6:7]
	v_pk_add_f32 v[0:1], v[0:1], v[4:5]
	global_store_dwordx4 v[16:17], v[0:3], off offset:528
